# v30: v29 with the HGRN scan on XCDs 4-5 and the weight conversion on XCDs 6-7 (GDN scan + helpers stay on XCDs 0-3)
# baseline (speedup 1.0000x reference)
.LBB0_256:
	s_mov_b32 s100, s64
	s_lshr_b32 s98, s64, 6
	s_xor_b32 s98, s98, s64
	s_lshr_b32 s99, s64, 1
	s_and_b32 s98, s98, s99
	s_and_b32 s98, s98, 2
	s_lshl_b32 s99, s98, 6
	s_or_b32 s98, s98, s99
	s_xor_b32 s64, s64, s98
	s_and_b32 s98, s64, 3
	s_lshl_b32 s98, s98, 1
	s_bfe_u32 s99, s64, 0x10003
	s_or_b32 s98, s98, s99
	s_bfe_u32 s99, s64, 0x30004
	s_lshl_b32 s99, s99, 3
	s_or_b32 s98, s98, s99
	s_bfe_u32 s99, s64, 0x10002
	s_lshl_b32 s101, s99, 7
	s_sub_i32 s101, 0xc0, s101
	s_lshl_b32 s99, s99, 6
	s_add_i32 s98, s98, s99
	s_bfe_u32 s99, s64, 0x10007
	s_mul_i32 s99, s99, s101
	s_add_i32 s64, s98, s99
	v_readlane_b32 s8, v253, 41
	s_cmp_lt_i32 s66, 5
	v_readlane_b32 s22, v253, 55
	s_cselect_b64 s[4:5], -1, 0
	v_readlane_b32 s23, v253, 56
	s_add_u32 s28, s22, 0x2200000
	s_addc_u32 s29, s23, 0
	s_add_u32 s26, s22, 0x2a00000
	s_addc_u32 s27, s23, 0
	s_add_u32 s24, s22, 0x4a00000
	s_addc_u32 s25, s23, 0
	s_and_b64 s[30:31], s[4:5], s[2:3]
	s_andn2_b64 vcc, exec, s[30:31]
	v_readlane_b32 s9, v253, 42
	v_readlane_b32 s10, v253, 43
	v_readlane_b32 s11, v253, 44
	v_readlane_b32 s12, v253, 45
	v_readlane_b32 s13, v253, 46
	v_readlane_b32 s14, v253, 47
	v_readlane_b32 s15, v253, 48
	v_readlane_b32 s16, v253, 49
	v_readlane_b32 s17, v253, 50
	v_readlane_b32 s18, v253, 51
	v_readlane_b32 s19, v253, 52
	v_readlane_b32 s20, v253, 53
	v_readlane_b32 s21, v253, 54
	s_cbranch_vccnz .LBB0_377
	s_and_b32 s2, s64, 0xffffffc0
	s_cmpk_lg_i32 s2, 0x80
	s_cbranch_scc1 .LBB0_303
	s_lshl_b32 s2, s64, 3
	s_add_i32 s2, s2, s91
	s_add_i32 s41, s2, 0xfffffc00
	s_cmpk_lt_i32 s41, 0x4800
	s_cselect_b64 s[18:19], -1, 0
	s_and_b64 vcc, exec, s[18:19]
	v_lshrrev_b32_e32 v1, 5, v170
	v_and_b32_e32 v52, 31, v0
	s_cbranch_vccnz .LBB0_261
	v_lshrrev_b32_e32 v53, 5, v170
	v_and_b32_e32 v42, 31, v0
	v_mov_b32_e32 v43, 0
	s_cbranch_execz .LBB0_262
	s_waitcnt vmcnt(0)
	v_mov_b32_e32 v2, 0
	v_mov_b32_e32 v3, v2
	v_mov_b32_e32 v4, v2
	v_mov_b32_e32 v5, v2
	v_mov_b32_e32 v6, v2
	v_mov_b32_e32 v7, v2
	v_mov_b32_e32 v8, v2
	v_mov_b32_e32 v9, v2
	v_mov_b32_e32 v44, v2
	v_mov_b32_e32 v45, v2
	v_mov_b32_e32 v46, v2
	v_mov_b32_e32 v47, v2
	v_mov_b32_e32 v48, v2
	v_mov_b32_e32 v49, v2
	v_mov_b32_e32 v50, v2
	v_mov_b32_e32 v51, v2
	v_mov_b32_e32 v56, v2
	v_mov_b32_e32 v57, v2
	v_mov_b32_e32 v58, v2
	v_mov_b32_e32 v59, v2
	v_mov_b32_e32 v60, v2
	v_mov_b32_e32 v61, v2
	v_mov_b32_e32 v94, v2
	v_mov_b32_e32 v95, v2
	v_mov_b32_e32 v96, v2
	v_mov_b32_e32 v97, v2
	v_mov_b32_e32 v98, v2
	v_mov_b32_e32 v99, v2
	v_mov_b32_e32 v100, v2
	v_mov_b32_e32 v101, v2
	v_mov_b32_e32 v102, v2
	v_mov_b32_e32 v103, v2
	v_mov_b32_e32 v1, v53
	v_mov_b32_e32 v52, v42
	s_branch .LBB0_272
